# v100 + static s_setprio 1 for waves 4-7 in the four GEMM tile bodies (reset to 0 at the per-tile pull barrier)
# speedup vs baseline: 1.0030x; 1.0030x over previous
.LBB0_124:
	s_or_b64 exec, exec, s[10:11]
	s_waitcnt lgkmcnt(0)
	s_setprio 0
	s_barrier
	ds_read_b32 v0, v230
	s_waitcnt lgkmcnt(0)
	v_cmp_gt_i32_e32 vcc, 0, v0
	v_readfirstlane_b32 s10, v0
	s_cbranch_vccnz .LBB0_147
	s_and_b32 s34, s10, 63
	s_lshl_b32 s10, s10, 2
	s_and_b32 s25, s10, 0x7fffff00
	s_cmp_eq_u32 s34, 63
	s_mov_b64 s[10:11], -1
	s_cbranch_scc1 .LBB0_149
	v_mov_b32_e32 v203, v195
	v_readfirstlane_b32 s10, v195
	s_cmpk_lt_u32 s10, 0x100
	s_cbranch_scc1 .Lprio_ip
	s_setprio 1
.Lprio_ip:
	s_movk_i32 s10, 0x78
	v_lshrrev_b32_e32 v1, 1, v203
	v_and_b32_e32 v1, 6, v1
	v_bfe_u32 v201, v203, 4, 2
	v_lshrrev_b32_e64 v1, v1, s10
	v_bitop3_b32 v1, v1, v201, 3 bitop3:0x6c
	v_lshlrev_b32_e32 v0, 1, v201
	v_lshlrev_b32_e32 v10, 4, v1
	v_ashrrev_i32_e32 v1, 1, v203
	v_ashrrev_i32_e32 v8, 6, v203
	v_lshrrev_b32_e64 v22, v0, s10
	v_and_b32_e32 v238, 15, v203
	v_and_b32_e32 v239, 0xffffff80, v1
	v_xor_b32_e32 v0, v22, v203
	v_bfe_u32 v24, v203, 2, 4
	v_or_b32_e32 v1, v239, v238
	v_lshlrev_b32_e32 v18, 4, v8
	v_lshl_or_b32 v240, v1, 6, v10
	v_lshlrev_b32_e32 v1, 6, v203
	v_lshlrev_b32_e32 v0, 4, v0
	v_ashrrev_i32_e32 v19, 31, v18
	v_or_b32_e32 v4, s25, v24
	v_mov_b32_e32 v5, v17
	v_and_b32_e32 v11, 0x33c0, v1
	v_and_b32_e32 v0, 48, v0
	v_mov_b32_e32 v1, v17
	v_lshl_add_u64 v[6:7], v[4:5], 0, v[18:19]
	v_lshlrev_b32_e32 v241, 10, v8
	v_lshl_add_u64 v[2:3], s[4:5], 0, v[0:1]
	v_lshlrev_b64 v[6:7], 6, v[6:7]
	v_readfirstlane_b32 s10, v241
	v_lshl_add_u64 v[6:7], v[2:3], 0, v[6:7]
	s_mov_b32 m0, s10
	v_add_u32_e32 v8, 8, v8
	global_load_lds_dwordx4 v[6:7], off
	v_lshlrev_b32_e32 v6, 4, v8
	v_ashrrev_i32_e32 v7, 31, v6
	v_lshl_add_u64 v[4:5], v[4:5], 0, v[6:7]
	v_lshlrev_b32_e32 v242, 10, v8
	s_lshl_b32 s34, s34, 8
	v_lshlrev_b64 v[4:5], 6, v[4:5]
	v_readfirstlane_b32 s10, v242
	v_readlane_b32 s40, v252, 19
	v_lshl_add_u64 v[4:5], v[2:3], 0, v[4:5]
	s_mov_b32 m0, s10
	v_or_b32_e32 v20, s34, v24
	v_mov_b32_e32 v21, v17
	v_readlane_b32 s41, v252, 20
	global_load_lds_dwordx4 v[4:5], off
	v_lshl_add_u64 v[4:5], v[20:21], 0, v[18:19]
	v_add_u32_e32 v8, 0x4000, v241
	v_lshl_add_u64 v[0:1], s[40:41], 0, v[0:1]
	v_lshlrev_b64 v[4:5], 6, v[4:5]
	v_readfirstlane_b32 s10, v8
	v_lshl_add_u64 v[4:5], v[0:1], 0, v[4:5]
	s_mov_b32 m0, s10
	v_add_u32_e32 v8, 0x4000, v242
	global_load_lds_dwordx4 v[4:5], off
	v_lshl_add_u64 v[4:5], v[20:21], 0, v[6:7]
	v_lshlrev_b64 v[4:5], 6, v[4:5]
	v_readfirstlane_b32 s10, v8
	v_lshl_add_u64 v[4:5], v[0:1], 0, v[4:5]
	s_mov_b32 m0, s10
	s_add_i32 s10, s25, 0x9000
	global_load_lds_dwordx4 v[4:5], off
	v_or_b32_e32 v4, s10, v24
	v_mov_b32_e32 v5, v17
	v_lshl_add_u64 v[8:9], v[4:5], 0, v[18:19]
	v_add_u32_e32 v12, 0x8000, v241
	v_lshlrev_b64 v[8:9], 6, v[8:9]
	v_readfirstlane_b32 s10, v12
	v_lshl_add_u64 v[8:9], v[2:3], 0, v[8:9]
	s_mov_b32 m0, s10
	v_lshl_add_u64 v[4:5], v[4:5], 0, v[6:7]
	global_load_lds_dwordx4 v[8:9], off
	v_add_u32_e32 v8, 0x8000, v242
	v_lshlrev_b64 v[4:5], 6, v[4:5]
	v_readfirstlane_b32 s10, v8
	v_lshl_add_u64 v[4:5], v[2:3], 0, v[4:5]
	s_mov_b32 m0, s10
	s_add_i32 s10, s34, 0xc80
	global_load_lds_dwordx4 v[4:5], off
	v_or_b32_e32 v4, s10, v24
	v_mov_b32_e32 v5, v17
	v_lshl_add_u64 v[8:9], v[4:5], 0, v[18:19]
	v_add_u32_e32 v12, 0xc000, v241
	v_lshlrev_b64 v[8:9], 6, v[8:9]
	v_readfirstlane_b32 s10, v12
	v_lshl_add_u64 v[8:9], v[0:1], 0, v[8:9]
	s_mov_b32 m0, s10
	v_lshl_add_u64 v[4:5], v[4:5], 0, v[6:7]
	global_load_lds_dwordx4 v[8:9], off
	v_add_u32_e32 v8, 0xc000, v242
	v_lshlrev_b64 v[4:5], 6, v[4:5]
	v_readfirstlane_b32 s10, v8
	v_lshl_add_u64 v[4:5], v[0:1], 0, v[4:5]
	s_mov_b32 m0, s10
	s_add_i32 s10, s25, 0x12000
	global_load_lds_dwordx4 v[4:5], off
	v_or_b32_e32 v4, s10, v24
	v_mov_b32_e32 v5, v17
	v_lshl_add_u64 v[8:9], v[4:5], 0, v[18:19]
	v_add_u32_e32 v12, 0x10000, v241
	v_lshlrev_b64 v[8:9], 6, v[8:9]
	v_readfirstlane_b32 s10, v12
	v_lshl_add_u64 v[8:9], v[2:3], 0, v[8:9]
	s_mov_b32 m0, s10
	v_lshl_add_u64 v[4:5], v[4:5], 0, v[6:7]
	global_load_lds_dwordx4 v[8:9], off
	v_add_u32_e32 v8, 0x10000, v242
	v_lshlrev_b64 v[4:5], 6, v[4:5]
	v_readfirstlane_b32 s10, v8
	v_lshl_add_u64 v[4:5], v[2:3], 0, v[4:5]
	s_mov_b32 m0, s10
	s_add_i32 s10, s34, 0x1900
	global_load_lds_dwordx4 v[4:5], off
	v_or_b32_e32 v4, s10, v24
	v_mov_b32_e32 v5, v17
	v_lshl_add_u64 v[8:9], v[4:5], 0, v[18:19]
	v_add_u32_e32 v12, 0x14000, v241
	v_lshlrev_b64 v[8:9], 6, v[8:9]
	v_readfirstlane_b32 s10, v12
	v_lshl_add_u64 v[8:9], v[0:1], 0, v[8:9]
	s_mov_b32 m0, s10
	v_lshl_add_u64 v[4:5], v[4:5], 0, v[6:7]
	global_load_lds_dwordx4 v[8:9], off
	v_add_u32_e32 v8, 0x14000, v242
	v_lshlrev_b64 v[4:5], 6, v[4:5]
	v_readfirstlane_b32 s10, v8
	v_lshl_add_u64 v[4:5], v[0:1], 0, v[4:5]
	s_mov_b32 m0, s10
	s_add_i32 s10, s25, 0x1b000
	global_load_lds_dwordx4 v[4:5], off
	v_or_b32_e32 v4, s10, v24
	v_mov_b32_e32 v5, v17
	v_lshl_add_u64 v[8:9], v[4:5], 0, v[18:19]
	v_lshl_add_u64 v[4:5], v[4:5], 0, v[6:7]
	v_lshlrev_b64 v[8:9], 6, v[8:9]
	v_add_u32_e32 v12, 0x18000, v241
	v_lshlrev_b64 v[4:5], 6, v[4:5]
	v_lshl_add_u64 v[8:9], v[2:3], 0, v[8:9]
	v_readfirstlane_b32 s10, v12
	v_lshl_add_u64 v[2:3], v[2:3], 0, v[4:5]
	v_add_u32_e32 v4, 0x18000, v242
	s_mov_b32 m0, s10
	v_readfirstlane_b32 s10, v4
	global_load_lds_dwordx4 v[8:9], off
	s_mov_b32 m0, s10
	s_add_i32 s10, s34, 0x2580
	global_load_lds_dwordx4 v[2:3], off
	v_or_b32_e32 v2, s10, v24
	v_mov_b32_e32 v3, v17
	v_lshl_add_u64 v[4:5], v[2:3], 0, v[18:19]
	v_lshl_add_u64 v[2:3], v[2:3], 0, v[6:7]
	v_lshlrev_b64 v[4:5], 6, v[4:5]
	v_add_u32_e32 v8, 0x1c000, v241
	v_lshlrev_b64 v[2:3], 6, v[2:3]
	v_lshl_add_u64 v[4:5], v[0:1], 0, v[4:5]
	v_readfirstlane_b32 s10, v8
	v_lshl_add_u64 v[0:1], v[0:1], 0, v[2:3]
	v_add_u32_e32 v2, 0x1c000, v242
	s_mov_b32 m0, s10
	v_readfirstlane_b32 s10, v2
	global_load_lds_dwordx4 v[4:5], off
	s_mov_b32 m0, s10
	s_movk_i32 s10, 0x4000
	global_load_lds_dwordx4 v[0:1], off
	v_or3_b32 v243, v11, v10, s10
	s_waitcnt vmcnt(12)
	s_barrier
	ds_read_b128 v[0:3], v243 offset:0
	ds_read_b128 v[4:7], v243 offset:1024
	ds_read_b128 v[8:11], v243 offset:2048
	ds_read_b128 v[12:15], v243 offset:3072
	v_bitop3_b32 v21, v22, 3, v203 bitop3:0x48
	ds_read_b128 v[58:61], v240 offset:0
	v_lshlrev_b32_e32 v206, 4, v21
	v_add_u32_e32 v22, 0x3e80, v20
	v_mov_b32_e32 v23, v17
	v_add_u32_e32 v20, 0x3200, v20
	v_mov_b32_e32 v21, v17
	ds_read_b128 v[54:57], v240 offset:1024
	v_lshl_add_u64 v[22:23], v[18:19], 0, v[22:23]
	v_lshl_add_u64 v[20:21], v[18:19], 0, v[20:21]
	ds_read_b128 v[50:53], v240 offset:2048
	v_lshlrev_b64 v[22:23], 6, v[22:23]
	v_add_u32_e32 v24, s25, v24
	v_lshlrev_b64 v[20:21], 6, v[20:21]
	ds_read_b128 v[38:41], v240 offset:3072
	v_lshl_add_u64 v[208:209], s[40:41], 0, v[22:23]
	v_add_u32_e32 v22, 0x2d000, v24
	v_mov_b32_e32 v23, v17
	v_lshl_add_u64 v[212:213], s[40:41], 0, v[20:21]
	v_add_u32_e32 v20, 0x24000, v24
	v_mov_b32_e32 v21, v17
	s_waitcnt lgkmcnt(0)
	v_lshl_add_u64 v[22:23], v[18:19], 0, v[22:23]
	v_lshl_add_u64 v[18:19], v[18:19], 0, v[20:21]
	v_lshlrev_b64 v[22:23], 6, v[22:23]
	v_lshlrev_b64 v[18:19], 6, v[18:19]
	v_mov_b32_e32 v74, 0
	v_mov_b32_e32 v207, v17
	v_lshl_add_u64 v[210:211], s[40:41], 0, v[22:23]
	v_lshl_add_u64 v[214:215], s[40:41], 0, v[18:19]
	s_mov_b32 s42, 0
	s_mov_b32 s44, 29
	s_mov_b32 s45, 0
	v_mov_b32_e32 v75, v74
	v_mov_b32_e32 v76, v74
	v_mov_b32_e32 v77, v74
	v_mov_b32_e32 v90, v74
	v_mov_b32_e32 v91, v74
	v_mov_b32_e32 v92, v74
	v_mov_b32_e32 v93, v74
	v_mov_b32_e32 v98, v74
	v_mov_b32_e32 v99, v74
	v_mov_b32_e32 v100, v74
	v_mov_b32_e32 v101, v74
	v_mov_b32_e32 v18, v74
	v_mov_b32_e32 v19, v74
	v_mov_b32_e32 v20, v74
	v_mov_b32_e32 v21, v74
	v_mov_b32_e32 v22, v74
	v_mov_b32_e32 v23, v74
	v_mov_b32_e32 v24, v74
	v_mov_b32_e32 v25, v74
	v_mov_b32_e32 v26, v74
	v_mov_b32_e32 v27, v74
	v_mov_b32_e32 v28, v74
	v_mov_b32_e32 v29, v74
	v_mov_b32_e32 v30, v74
	v_mov_b32_e32 v31, v74
	v_mov_b32_e32 v32, v74
	v_mov_b32_e32 v33, v74
	v_mov_b32_e32 v34, v74
	v_mov_b32_e32 v35, v74
	v_mov_b32_e32 v36, v74
	v_mov_b32_e32 v37, v74
	v_mov_b32_e32 v42, v74
	v_mov_b32_e32 v43, v74
	v_mov_b32_e32 v44, v74
	v_mov_b32_e32 v45, v74
	v_mov_b32_e32 v46, v74
	v_mov_b32_e32 v47, v74
	v_mov_b32_e32 v48, v74
	v_mov_b32_e32 v49, v74
	v_mov_b32_e32 v62, v74
	v_mov_b32_e32 v63, v74
	v_mov_b32_e32 v64, v74
	v_mov_b32_e32 v65, v74
	v_mov_b32_e32 v66, v74
	v_mov_b32_e32 v67, v74
	v_mov_b32_e32 v68, v74
	v_mov_b32_e32 v69, v74
	v_mov_b32_e32 v70, v74
	v_mov_b32_e32 v71, v74
	v_mov_b32_e32 v72, v74
	v_mov_b32_e32 v73, v74
	v_mov_b32_e32 v78, v74
	v_mov_b32_e32 v79, v74
	v_mov_b32_e32 v80, v74
	v_mov_b32_e32 v81, v74
	v_mov_b32_e32 v82, v74
	v_mov_b32_e32 v83, v74
	v_mov_b32_e32 v84, v74
	v_mov_b32_e32 v85, v74
	v_mov_b32_e32 v94, v74
	v_mov_b32_e32 v95, v74
	v_mov_b32_e32 v96, v74
	v_mov_b32_e32 v97, v74
	v_mov_b32_e32 v86, v74
	v_mov_b32_e32 v87, v74
	v_mov_b32_e32 v88, v74
	v_mov_b32_e32 v89, v74
	v_mov_b32_e32 v102, v74
	v_mov_b32_e32 v103, v74
	v_mov_b32_e32 v104, v74
	v_mov_b32_e32 v105, v74
	v_mov_b32_e32 v106, v74
	v_mov_b32_e32 v107, v74
	v_mov_b32_e32 v108, v74
	v_mov_b32_e32 v109, v74
	v_mov_b32_e32 v110, v74
	v_mov_b32_e32 v111, v74
	v_mov_b32_e32 v112, v74
	v_mov_b32_e32 v113, v74
	v_mov_b32_e32 v114, v74
	v_mov_b32_e32 v115, v74
	v_mov_b32_e32 v116, v74
	v_mov_b32_e32 v117, v74
	v_mov_b32_e32 v118, v74
	v_mov_b32_e32 v119, v74
	v_mov_b32_e32 v120, v74
	v_mov_b32_e32 v121, v74
	v_mov_b32_e32 v122, v74
	v_mov_b32_e32 v123, v74
	v_mov_b32_e32 v124, v74
	v_mov_b32_e32 v125, v74
	v_mov_b32_e32 v126, v74
	v_mov_b32_e32 v127, v74
	v_mov_b32_e32 v128, v74
	v_mov_b32_e32 v129, v74
	v_mov_b32_e32 v130, v74
	v_mov_b32_e32 v131, v74
	v_mov_b32_e32 v132, v74
	v_mov_b32_e32 v133, v74
	v_mov_b32_e32 v134, v74
	v_mov_b32_e32 v135, v74
	v_mov_b32_e32 v136, v74
	v_mov_b32_e32 v137, v74
	v_mov_b32_e32 v138, v74
	v_mov_b32_e32 v139, v74
	v_mov_b32_e32 v140, v74
	v_mov_b32_e32 v141, v74
	v_mov_b32_e32 v142, v74
	v_mov_b32_e32 v143, v74
	v_mov_b32_e32 v144, v74
	v_mov_b32_e32 v145, v74
	v_mov_b32_e32 v146, v74
	v_mov_b32_e32 v147, v74
	v_mov_b32_e32 v148, v74
	v_mov_b32_e32 v149, v74
	v_mov_b32_e32 v150, v74
	v_mov_b32_e32 v151, v74
	v_mov_b32_e32 v152, v74
	v_mov_b32_e32 v153, v74
	v_mov_b32_e32 v154, v74
	v_mov_b32_e32 v155, v74
	v_mov_b32_e32 v156, v74
	v_mov_b32_e32 v157, v74
	v_mov_b32_e32 v158, v74
	v_mov_b32_e32 v159, v74
	v_mov_b32_e32 v160, v74
	v_mov_b32_e32 v161, v74
	v_readfirstlane_b32 s100, v241
	v_readfirstlane_b32 s101, v242
	s_branch .LBB0_128

.LBB0_966:
	s_or_b64 exec, exec, s[44:45]
	s_waitcnt lgkmcnt(0)
	s_setprio 0
	s_barrier
	ds_read_b32 v0, v230
	s_waitcnt lgkmcnt(0)
	v_cmp_gt_i32_e32 vcc, 0, v0
	v_readfirstlane_b32 s25, v0
	s_cbranch_vccnz .LBB0_998
	v_mov_b32_e32 v128, v195
	v_readfirstlane_b32 s43, v195
	s_cmpk_lt_u32 s43, 0x100
	s_cbranch_scc1 .Lprio_op
	s_setprio 1
.Lprio_op:
	s_movk_i32 s43, 0x78
	v_lshrrev_b32_e32 v1, 1, v128
	v_and_b32_e32 v1, 6, v1
	s_lshl_b32 s34, s25, 2
	s_lshl_b32 s25, s25, 7
	v_bfe_u32 v127, v128, 4, 2
	v_lshrrev_b32_e64 v1, v1, s43
	s_and_b32 s34, s34, 0x7fffff00
	s_and_b32 s25, s25, 0x1f80
	v_ashrrev_i32_e32 v6, 6, v128
	v_lshlrev_b32_e32 v0, 1, v127
	s_waitcnt vmcnt(0)
	v_bfe_u32 v2, v128, 2, 4
	v_bitop3_b32 v1, v1, v127, 3 bitop3:0x6c
	v_lshrrev_b32_e64 v74, v0, s43
	v_lshlrev_b32_e32 v12, 4, v1
	v_ashrrev_i32_e32 v1, 1, v128
	v_or_b32_e32 v7, s34, v2
	v_or_b32_e32 v2, s25, v2
	v_lshlrev_b32_e32 v8, 4, v6
	v_xor_b32_e32 v0, v74, v128
	v_and_b32_e32 v129, 15, v128
	v_and_b32_e32 v130, 0xffffffc0, v1
	v_add_u32_e32 v2, v2, v8
	v_or_b32_e32 v1, v130, v129
	v_lshlrev_b32_e32 v0, 4, v0
	v_ashrrev_i32_e32 v3, 31, v2
	v_readlane_b32 s44, v252, 61
	v_lshl_or_b32 v131, v1, 6, v12
	v_and_b32_e32 v0, 48, v0
	v_mov_b32_e32 v1, v17
	v_lshlrev_b64 v[86:87], 11, v[2:3]
	v_readlane_b32 s45, v252, 62
	v_lshlrev_b32_e32 v132, 10, v6
	v_add_u32_e32 v6, 8, v6
	v_lshl_add_u64 v[4:5], s[0:1], 0, v[0:1]
	v_lshl_add_u64 v[2:3], s[44:45], 0, v[86:87]
	v_add_u32_e32 v75, v7, v8
	v_readfirstlane_b32 s49, v132
	v_lshlrev_b32_e32 v133, 10, v6
	v_lshl_add_u64 v[0:1], v[2:3], 0, v[0:1]
	v_mad_i64_i32 v[2:3], s[44:45], v75, s33, v[4:5]
	s_mov_b32 m0, s49
	v_lshl_add_u32 v7, v6, 4, v7
	v_readfirstlane_b32 s51, v133
	v_add_u32_e32 v6, 0x4000, v132
	global_load_lds_dwordx4 v[2:3], off
	v_mad_i64_i32 v[4:5], s[44:45], v7, s33, v[4:5]
	s_mov_b32 m0, s51
	v_readfirstlane_b32 s50, v6
	v_add_u32_e32 v8, 0x6000, v132
	global_load_lds_dwordx4 v[4:5], off
	s_mov_b32 m0, s50
	v_readfirstlane_b32 s46, v8
	v_add_u32_e32 v8, 0x6000, v133
	global_load_lds_dwordx4 v[0:1], off
	v_lshl_add_u64 v[6:7], v[2:3], 0, 64
	s_mov_b32 m0, s46
	v_readfirstlane_b32 s47, v8
	v_add_u32_e32 v8, 0xa000, v132
	global_load_lds_dwordx4 v[6:7], off
	v_lshl_add_u64 v[6:7], v[4:5], 0, 64
	s_mov_b32 m0, s47
	v_readfirstlane_b32 s48, v8
	v_add_u32_e32 v8, 0xc000, v132
	global_load_lds_dwordx4 v[6:7], off
	v_lshl_add_u64 v[6:7], v[0:1], 0, 64
	s_mov_b32 m0, s48
	s_mov_b64 s[52:53], 0x80
	v_readfirstlane_b32 s43, v8
	v_add_u32_e32 v8, 0xc000, v133
	global_load_lds_dwordx4 v[6:7], off
	v_lshl_add_u64 v[6:7], v[2:3], 0, s[52:53]
	s_mov_b32 m0, s43
	v_readfirstlane_b32 s44, v8
	v_add_u32_e32 v8, 0x10000, v132
	global_load_lds_dwordx4 v[6:7], off
	v_lshl_add_u64 v[6:7], v[4:5], 0, s[52:53]
	s_mov_b32 m0, s44
	v_readfirstlane_b32 s45, v8
	global_load_lds_dwordx4 v[6:7], off
	v_lshl_add_u64 v[6:7], v[0:1], 0, s[52:53]
	s_mov_b32 m0, s45
	s_mov_b64 s[52:53], 0xc0
	global_load_lds_dwordx4 v[6:7], off
	v_add_u32_e32 v6, 0x12000, v132
	v_add_u32_e32 v7, 0x12000, v133
	v_readfirstlane_b32 s58, v6
	v_lshl_add_u64 v[8:9], v[2:3], 0, s[52:53]
	s_mov_b32 m0, s58
	v_readfirstlane_b32 s59, v7
	global_load_lds_dwordx4 v[8:9], off
	v_lshl_add_u64 v[8:9], v[4:5], 0, s[52:53]
	s_mov_b32 m0, s59
	v_lshl_add_u64 v[10:11], v[0:1], 0, s[52:53]
	global_load_lds_dwordx4 v[8:9], off
	v_add_u32_e32 v8, 0x16000, v132
	v_add_u32_e32 v9, 0x18000, v132
	v_readfirstlane_b32 s60, v8
	s_mov_b32 m0, s60
	s_mov_b64 s[52:53], 0x100
	v_readfirstlane_b32 s55, v9
	v_add_u32_e32 v9, 0x18000, v133
	global_load_lds_dwordx4 v[10:11], off
	v_lshl_add_u64 v[10:11], v[2:3], 0, s[52:53]
	s_mov_b32 m0, s55
	v_readfirstlane_b32 s56, v9
	v_add_u32_e32 v9, 0x1c000, v132
	global_load_lds_dwordx4 v[10:11], off
	v_lshl_add_u64 v[10:11], v[4:5], 0, s[52:53]
	s_mov_b32 m0, s56
	v_readfirstlane_b32 s57, v9
	v_add_u32_e32 v9, 0x1e000, v132
	global_load_lds_dwordx4 v[10:11], off
	v_lshl_add_u64 v[10:11], v[0:1], 0, s[52:53]
	s_mov_b32 m0, s57
	s_mov_b64 s[62:63], 0x140
	v_readfirstlane_b32 s52, v9
	v_add_u32_e32 v9, 0x1e000, v133
	global_load_lds_dwordx4 v[10:11], off
	v_lshl_add_u64 v[10:11], v[2:3], 0, s[62:63]
	s_mov_b32 m0, s52
	v_readfirstlane_b32 s53, v9
	v_add_u32_e32 v9, 0x22000, v132
	global_load_lds_dwordx4 v[10:11], off
	v_lshl_add_u64 v[10:11], v[4:5], 0, s[62:63]
	s_mov_b32 m0, s53
	v_readfirstlane_b32 s54, v9
	v_lshlrev_b32_e32 v13, 6, v128
	global_load_lds_dwordx4 v[10:11], off
	v_lshl_add_u64 v[10:11], v[0:1], 0, s[62:63]
	s_mov_b32 m0, s54
	s_movk_i32 s61, 0x13c0
	global_load_lds_dwordx4 v[10:11], off
	v_and_or_b32 v9, v13, s61, v12
	v_or_b32_e32 v134, 0x4000, v9
	s_waitcnt vmcnt(15)
	s_barrier
	ds_read_b128 v[10:13], v134 offset:0
	ds_read_b128 v[18:21], v134 offset:1024
	ds_read_b128 v[22:25], v134 offset:2048
	ds_read_b128 v[26:29], v134 offset:3072
	ds_read_b128 v[30:33], v131 offset:0
	ds_read_b128 v[34:37], v131 offset:1024
	s_mov_b64 s[62:63], 0x180
	s_waitcnt lgkmcnt(0)
	ds_read_b128 v[58:61], v131 offset:2048
	ds_read_b128 v[66:69], v131 offset:3072
	v_lshl_add_u64 v[14:15], v[2:3], 0, s[62:63]
	s_waitcnt lgkmcnt(0)
	s_mov_b32 m0, s49
	s_waitcnt vmcnt(12)
	s_barrier
	global_load_lds_dwordx4 v[14:15], off
	v_lshl_add_u64 v[14:15], v[4:5], 0, s[62:63]
	s_mov_b32 m0, s51
	v_or_b32_e32 v85, 0xa000, v9
	global_load_lds_dwordx4 v[14:15], off
	v_lshl_add_u64 v[14:15], v[0:1], 0, s[62:63]
	s_mov_b32 m0, s50
	v_mfma_f32_16x16x32_bf16 v[38:41], v[10:13], v[30:33], 0
	global_load_lds_dwordx4 v[14:15], off
	ds_read_b128 v[88:91], v85 offset:0
	ds_read_b128 v[92:95], v85 offset:1024
	ds_read_b128 v[96:99], v85 offset:2048
	ds_read_b128 v[100:103], v85 offset:3072
	v_mfma_f32_16x16x32_bf16 v[42:45], v[18:21], v[30:33], 0
	v_add_u32_e32 v84, 0x6000, v131
	ds_read_b128 v[104:107], v84 offset:0
	ds_read_b128 v[108:111], v84 offset:1024
	v_mfma_f32_16x16x32_bf16 v[46:49], v[22:25], v[30:33], 0
	s_waitcnt lgkmcnt(0)
	s_mov_b64 s[62:63], 0x1c0
	v_lshl_add_u64 v[14:15], v[2:3], 0, s[62:63]
	v_mfma_f32_16x16x32_bf16 v[30:33], v[26:29], v[30:33], 0
	s_mov_b32 m0, s46
	v_or_b32_e32 v117, 0x10000, v9
	v_add_u32_e32 v116, 0xc000, v131
	v_mfma_f32_16x16x32_bf16 v[50:53], v[10:13], v[34:37], 0
	v_or_b32_e32 v125, 0x16000, v9
	v_add_u32_e32 v124, 0x12000, v131
	v_or_b32_e32 v144, 0x1c000, v9
	v_mfma_f32_16x16x32_bf16 v[54:57], v[18:21], v[34:37], 0
	v_add_u32_e32 v135, 0x18000, v131
	v_or_b32_e32 v9, 0x22000, v9
	v_bitop3_b32 v74, v74, 3, v128 bitop3:0x48
	v_mfma_f32_16x16x32_bf16 v[62:65], v[22:25], v[34:37], 0
	v_mfma_f32_16x16x32_bf16 v[34:37], v[26:29], v[34:37], 0
	v_mfma_f32_16x16x32_bf16 v[70:73], v[10:13], v[58:61], 0
	v_mfma_f32_16x16x32_bf16 v[76:79], v[18:21], v[58:61], 0
	v_mfma_f32_16x16x32_bf16 v[80:83], v[22:25], v[58:61], 0
	v_mfma_f32_16x16x32_bf16 v[58:61], v[26:29], v[58:61], 0
	v_mfma_f32_16x16x32_bf16 v[10:13], v[10:13], v[66:69], 0
	v_mfma_f32_16x16x32_bf16 v[18:21], v[18:21], v[66:69], 0
	v_mfma_f32_16x16x32_bf16 v[22:25], v[22:25], v[66:69], 0
	v_mfma_f32_16x16x32_bf16 v[26:29], v[26:29], v[66:69], 0
	ds_read_b128 v[66:69], v84 offset:2048
	v_mfma_f32_16x16x32_bf16 v[38:41], v[88:91], v[104:107], v[38:41]
	v_mfma_f32_16x16x32_bf16 v[42:45], v[92:95], v[104:107], v[42:45]
	v_mfma_f32_16x16x32_bf16 v[46:49], v[96:99], v[104:107], v[46:49]
	v_mfma_f32_16x16x32_bf16 v[30:33], v[100:103], v[104:107], v[30:33]
	ds_read_b128 v[104:107], v84 offset:3072
	s_nop 0
	s_waitcnt lgkmcnt(0)
	s_waitcnt vmcnt(12)
	s_barrier
	global_load_lds_dwordx4 v[14:15], off
	v_lshl_add_u64 v[14:15], v[4:5], 0, s[62:63]
	s_mov_b32 m0, s47
	v_mfma_f32_16x16x32_bf16 v[70:73], v[88:91], v[66:69], v[70:73]
	global_load_lds_dwordx4 v[14:15], off
	v_lshl_add_u64 v[14:15], v[0:1], 0, s[62:63]
	s_mov_b32 m0, s48
	v_mfma_f32_16x16x32_bf16 v[76:79], v[92:95], v[66:69], v[76:79]
	global_load_lds_dwordx4 v[14:15], off
	v_lshl_add_u64 v[14:15], v[2:3], 0, s[38:39]
	v_mfma_f32_16x16x32_bf16 v[80:83], v[96:99], v[66:69], v[80:83]
	s_mov_b32 m0, s43
	s_mov_b64 s[62:63], 0x240
	v_mfma_f32_16x16x32_bf16 v[58:61], v[100:103], v[66:69], v[58:61]
	ds_read_b128 v[66:69], v117 offset:0
	v_mfma_f32_16x16x32_bf16 v[50:53], v[88:91], v[108:111], v[50:53]
	v_mfma_f32_16x16x32_bf16 v[10:13], v[88:91], v[104:107], v[10:13]
	ds_read_b128 v[88:91], v117 offset:1024
	v_mfma_f32_16x16x32_bf16 v[54:57], v[92:95], v[108:111], v[54:57]
	v_mfma_f32_16x16x32_bf16 v[18:21], v[92:95], v[104:107], v[18:21]
	ds_read_b128 v[92:95], v117 offset:2048
	v_mfma_f32_16x16x32_bf16 v[62:65], v[96:99], v[108:111], v[62:65]
	v_mfma_f32_16x16x32_bf16 v[34:37], v[100:103], v[108:111], v[34:37]
	ds_read_b128 v[108:111], v117 offset:3072
	ds_read_b128 v[112:115], v116 offset:0
	v_mfma_f32_16x16x32_bf16 v[22:25], v[96:99], v[104:107], v[22:25]
	ds_read_b128 v[96:99], v116 offset:1024
	s_nop 0
	s_waitcnt lgkmcnt(0)
	v_mfma_f32_16x16x32_bf16 v[26:29], v[100:103], v[104:107], v[26:29]
	ds_read_b128 v[100:103], v116 offset:2048
	ds_read_b128 v[104:107], v116 offset:3072
	s_nop 0
	s_waitcnt lgkmcnt(0)
	s_waitcnt vmcnt(12)
	s_barrier
	global_load_lds_dwordx4 v[14:15], off
	v_lshl_add_u64 v[14:15], v[4:5], 0, s[38:39]
	s_mov_b32 m0, s44
	v_mfma_f32_16x16x32_bf16 v[38:41], v[66:69], v[112:115], v[38:41]
	global_load_lds_dwordx4 v[14:15], off
	v_lshl_add_u64 v[14:15], v[0:1], 0, s[38:39]
	s_mov_b32 m0, s45
	v_mfma_f32_16x16x32_bf16 v[50:53], v[66:69], v[96:99], v[50:53]
	global_load_lds_dwordx4 v[14:15], off
	v_lshl_add_u64 v[14:15], v[2:3], 0, s[62:63]
	v_mfma_f32_16x16x32_bf16 v[70:73], v[66:69], v[100:103], v[70:73]
	s_mov_b32 m0, s58
	v_mfma_f32_16x16x32_bf16 v[10:13], v[66:69], v[104:107], v[10:13]
	ds_read_b128 v[66:69], v125 offset:0
	v_mfma_f32_16x16x32_bf16 v[54:57], v[88:91], v[96:99], v[54:57]
	v_mfma_f32_16x16x32_bf16 v[62:65], v[92:95], v[96:99], v[62:65]
	v_mfma_f32_16x16x32_bf16 v[34:37], v[108:111], v[96:99], v[34:37]
	ds_read_b128 v[96:99], v125 offset:1024
	v_mfma_f32_16x16x32_bf16 v[42:45], v[88:91], v[112:115], v[42:45]
	v_mfma_f32_16x16x32_bf16 v[76:79], v[88:91], v[100:103], v[76:79]
	v_mfma_f32_16x16x32_bf16 v[18:21], v[88:91], v[104:107], v[18:21]
	ds_read_b128 v[88:91], v125 offset:2048
	v_mfma_f32_16x16x32_bf16 v[80:83], v[92:95], v[100:103], v[80:83]
	v_mfma_f32_16x16x32_bf16 v[58:61], v[108:111], v[100:103], v[58:61]
	ds_read_b128 v[100:103], v125 offset:3072
	v_mfma_f32_16x16x32_bf16 v[46:49], v[92:95], v[112:115], v[46:49]
	v_mfma_f32_16x16x32_bf16 v[30:33], v[108:111], v[112:115], v[30:33]
	ds_read_b128 v[112:115], v124 offset:0
	v_mfma_f32_16x16x32_bf16 v[22:25], v[92:95], v[104:107], v[22:25]
	ds_read_b128 v[92:95], v124 offset:1024
	s_nop 0
	s_waitcnt lgkmcnt(0)
	v_mfma_f32_16x16x32_bf16 v[26:29], v[108:111], v[104:107], v[26:29]
	ds_read_b128 v[104:107], v124 offset:2048
	ds_read_b128 v[108:111], v124 offset:3072
	s_nop 0
	s_waitcnt lgkmcnt(0)
	s_waitcnt vmcnt(12)
	s_barrier
	global_load_lds_dwordx4 v[14:15], off
	v_lshl_add_u64 v[14:15], v[4:5], 0, s[62:63]
	s_mov_b32 m0, s59
	v_mfma_f32_16x16x32_bf16 v[38:41], v[66:69], v[112:115], v[38:41]
	global_load_lds_dwordx4 v[14:15], off
	v_lshl_add_u64 v[14:15], v[0:1], 0, s[62:63]
	s_mov_b32 m0, s60
	v_mfma_f32_16x16x32_bf16 v[50:53], v[66:69], v[92:95], v[50:53]
	global_load_lds_dwordx4 v[14:15], off
	s_mov_b64 s[58:59], 0x280
	v_mfma_f32_16x16x32_bf16 v[70:73], v[66:69], v[104:107], v[70:73]
	v_lshl_add_u64 v[14:15], v[2:3], 0, s[58:59]
	s_mov_b32 m0, s55
	v_mfma_f32_16x16x32_bf16 v[10:13], v[66:69], v[108:111], v[10:13]
	ds_read_b128 v[66:69], v144 offset:0
	v_mfma_f32_16x16x32_bf16 v[54:57], v[96:99], v[92:95], v[54:57]
	v_mfma_f32_16x16x32_bf16 v[62:65], v[88:91], v[92:95], v[62:65]
	v_mfma_f32_16x16x32_bf16 v[34:37], v[100:103], v[92:95], v[34:37]
	ds_read_b128 v[92:95], v144 offset:1024
	v_mfma_f32_16x16x32_bf16 v[42:45], v[96:99], v[112:115], v[42:45]
	v_mfma_f32_16x16x32_bf16 v[76:79], v[96:99], v[104:107], v[76:79]
	v_mfma_f32_16x16x32_bf16 v[18:21], v[96:99], v[108:111], v[18:21]
	ds_read_b128 v[96:99], v144 offset:2048
	v_mfma_f32_16x16x32_bf16 v[80:83], v[88:91], v[104:107], v[80:83]
	v_mfma_f32_16x16x32_bf16 v[58:61], v[100:103], v[104:107], v[58:61]
	ds_read_b128 v[104:107], v144 offset:3072
	v_mfma_f32_16x16x32_bf16 v[46:49], v[88:91], v[112:115], v[46:49]
	v_mfma_f32_16x16x32_bf16 v[30:33], v[100:103], v[112:115], v[30:33]
	ds_read_b128 v[112:115], v135 offset:0
	v_mfma_f32_16x16x32_bf16 v[22:25], v[88:91], v[108:111], v[22:25]
	ds_read_b128 v[88:91], v135 offset:1024
	s_nop 0
	s_waitcnt lgkmcnt(0)
	v_mfma_f32_16x16x32_bf16 v[26:29], v[100:103], v[108:111], v[26:29]
	ds_read_b128 v[100:103], v135 offset:2048
	ds_read_b128 v[108:111], v135 offset:3072
	s_nop 0
	s_waitcnt lgkmcnt(0)
	s_waitcnt vmcnt(12)
	s_barrier
	global_load_lds_dwordx4 v[14:15], off
	v_lshl_add_u64 v[14:15], v[4:5], 0, s[58:59]
	s_mov_b32 m0, s56
	v_mfma_f32_16x16x32_bf16 v[38:41], v[66:69], v[112:115], v[38:41]
	global_load_lds_dwordx4 v[14:15], off
	v_lshl_add_u64 v[14:15], v[0:1], 0, s[58:59]
	s_mov_b32 m0, s57
	v_mfma_f32_16x16x32_bf16 v[50:53], v[66:69], v[88:91], v[50:53]
	global_load_lds_dwordx4 v[14:15], off
	v_add_u32_e32 v14, 0x1e000, v131
	v_mfma_f32_16x16x32_bf16 v[70:73], v[66:69], v[100:103], v[70:73]
	s_mov_b64 s[56:57], 0x2c0
	s_mov_b32 m0, s52
	v_mfma_f32_16x16x32_bf16 v[10:13], v[66:69], v[108:111], v[10:13]
	ds_read_b128 v[66:69], v9 offset:0
	v_mfma_f32_16x16x32_bf16 v[54:57], v[92:95], v[88:91], v[54:57]
	v_mfma_f32_16x16x32_bf16 v[62:65], v[96:99], v[88:91], v[62:65]
	v_mfma_f32_16x16x32_bf16 v[34:37], v[104:107], v[88:91], v[34:37]
	ds_read_b128 v[88:91], v9 offset:1024
	v_mfma_f32_16x16x32_bf16 v[42:45], v[92:95], v[112:115], v[42:45]
	v_mfma_f32_16x16x32_bf16 v[76:79], v[92:95], v[100:103], v[76:79]
	v_mfma_f32_16x16x32_bf16 v[18:21], v[92:95], v[108:111], v[18:21]
	ds_read_b128 v[92:95], v9 offset:2048
	v_mfma_f32_16x16x32_bf16 v[80:83], v[96:99], v[100:103], v[80:83]
	v_mfma_f32_16x16x32_bf16 v[58:61], v[104:107], v[100:103], v[58:61]
	ds_read_b128 v[100:103], v9 offset:3072
	v_mfma_f32_16x16x32_bf16 v[46:49], v[96:99], v[112:115], v[46:49]
	v_mfma_f32_16x16x32_bf16 v[30:33], v[104:107], v[112:115], v[30:33]
	ds_read_b128 v[112:115], v14 offset:0
	v_mfma_f32_16x16x32_bf16 v[22:25], v[96:99], v[108:111], v[22:25]
	ds_read_b128 v[96:99], v14 offset:1024
	s_nop 0
	s_waitcnt lgkmcnt(0)
	v_mfma_f32_16x16x32_bf16 v[26:29], v[104:107], v[108:111], v[26:29]
	ds_read_b128 v[104:107], v14 offset:2048
	ds_read_b128 v[108:111], v14 offset:3072
	v_lshl_add_u64 v[14:15], v[2:3], 0, s[56:57]
	s_waitcnt lgkmcnt(0)
	s_waitcnt vmcnt(12)
	s_barrier
	global_load_lds_dwordx4 v[14:15], off
	v_lshl_add_u64 v[14:15], v[4:5], 0, s[56:57]
	s_mov_b32 m0, s53
	v_mfma_f32_16x16x32_bf16 v[38:41], v[66:69], v[112:115], v[38:41]
	global_load_lds_dwordx4 v[14:15], off
	v_lshl_add_u64 v[14:15], v[0:1], 0, s[56:57]
	s_mov_b32 m0, s54
	v_mfma_f32_16x16x32_bf16 v[50:53], v[66:69], v[96:99], v[50:53]
	global_load_lds_dwordx4 v[14:15], off
	s_mov_b64 s[52:53], 0x300
	v_mfma_f32_16x16x32_bf16 v[70:73], v[66:69], v[104:107], v[70:73]
	v_lshl_add_u64 v[14:15], v[2:3], 0, s[52:53]
	s_mov_b32 m0, s49
	s_mov_b32 s56, 19
	v_mfma_f32_16x16x32_bf16 v[10:13], v[66:69], v[108:111], v[10:13]
	ds_read_b128 v[66:69], v134 offset:0
	v_mfma_f32_16x16x32_bf16 v[54:57], v[88:91], v[96:99], v[54:57]
	v_mfma_f32_16x16x32_bf16 v[62:65], v[92:95], v[96:99], v[62:65]
	v_mfma_f32_16x16x32_bf16 v[34:37], v[100:103], v[96:99], v[34:37]
	ds_read_b128 v[96:99], v134 offset:1024
	v_mfma_f32_16x16x32_bf16 v[42:45], v[88:91], v[112:115], v[42:45]
	v_mfma_f32_16x16x32_bf16 v[76:79], v[88:91], v[104:107], v[76:79]
	v_mfma_f32_16x16x32_bf16 v[18:21], v[88:91], v[108:111], v[18:21]
	ds_read_b128 v[88:91], v134 offset:2048
	v_mfma_f32_16x16x32_bf16 v[80:83], v[92:95], v[104:107], v[80:83]
	v_mfma_f32_16x16x32_bf16 v[58:61], v[100:103], v[104:107], v[58:61]
	ds_read_b128 v[104:107], v134 offset:3072
	v_mfma_f32_16x16x32_bf16 v[46:49], v[92:95], v[112:115], v[46:49]
	v_mfma_f32_16x16x32_bf16 v[30:33], v[100:103], v[112:115], v[30:33]
	ds_read_b128 v[112:115], v131 offset:0
	v_mfma_f32_16x16x32_bf16 v[22:25], v[92:95], v[108:111], v[22:25]
	ds_read_b128 v[92:95], v131 offset:1024
	s_nop 0
	s_waitcnt lgkmcnt(0)
	v_mfma_f32_16x16x32_bf16 v[26:29], v[100:103], v[108:111], v[26:29]
	ds_read_b128 v[100:103], v131 offset:2048
	ds_read_b128 v[108:111], v131 offset:3072
	s_nop 0
	s_waitcnt lgkmcnt(0)
	s_waitcnt vmcnt(12)
	s_barrier
	global_load_lds_dwordx4 v[14:15], off
	v_lshl_add_u64 v[14:15], v[4:5], 0, s[52:53]
	s_mov_b32 m0, s51
	v_mfma_f32_16x16x32_bf16 v[38:41], v[66:69], v[112:115], v[38:41]
	global_load_lds_dwordx4 v[14:15], off
	v_lshl_add_u64 v[14:15], v[0:1], 0, s[52:53]
	s_mov_b32 m0, s50
	v_mfma_f32_16x16x32_bf16 v[50:53], v[66:69], v[92:95], v[50:53]
	global_load_lds_dwordx4 v[14:15], off
	s_mov_b64 s[50:51], 0x340
	v_mfma_f32_16x16x32_bf16 v[70:73], v[66:69], v[100:103], v[70:73]
	v_lshl_add_u64 v[14:15], v[2:3], 0, s[50:51]
	s_mov_b32 m0, s46
	v_mfma_f32_16x16x32_bf16 v[10:13], v[66:69], v[108:111], v[10:13]
	ds_read_b128 v[66:69], v85 offset:0
	v_mfma_f32_16x16x32_bf16 v[54:57], v[96:99], v[92:95], v[54:57]
	v_mfma_f32_16x16x32_bf16 v[62:65], v[88:91], v[92:95], v[62:65]
	v_mfma_f32_16x16x32_bf16 v[34:37], v[104:107], v[92:95], v[34:37]
	ds_read_b128 v[92:95], v85 offset:1024
	v_mfma_f32_16x16x32_bf16 v[42:45], v[96:99], v[112:115], v[42:45]
	v_mfma_f32_16x16x32_bf16 v[76:79], v[96:99], v[100:103], v[76:79]
	v_mfma_f32_16x16x32_bf16 v[18:21], v[96:99], v[108:111], v[18:21]
	ds_read_b128 v[96:99], v85 offset:2048
	v_mfma_f32_16x16x32_bf16 v[80:83], v[88:91], v[100:103], v[80:83]
	v_mfma_f32_16x16x32_bf16 v[58:61], v[104:107], v[100:103], v[58:61]
	ds_read_b128 v[100:103], v85 offset:3072
	v_mfma_f32_16x16x32_bf16 v[46:49], v[88:91], v[112:115], v[46:49]
	v_mfma_f32_16x16x32_bf16 v[30:33], v[104:107], v[112:115], v[30:33]
	ds_read_b128 v[112:115], v84 offset:0
	v_mfma_f32_16x16x32_bf16 v[22:25], v[88:91], v[108:111], v[22:25]
	ds_read_b128 v[88:91], v84 offset:1024
	s_nop 0
	s_waitcnt lgkmcnt(0)
	v_mfma_f32_16x16x32_bf16 v[26:29], v[104:107], v[108:111], v[26:29]
	ds_read_b128 v[104:107], v84 offset:2048
	ds_read_b128 v[108:111], v84 offset:3072
	s_nop 0
	s_waitcnt lgkmcnt(0)
	s_waitcnt vmcnt(12)
	s_barrier
	global_load_lds_dwordx4 v[14:15], off
	v_lshl_add_u64 v[14:15], v[4:5], 0, s[50:51]
	s_mov_b32 m0, s47
	v_mfma_f32_16x16x32_bf16 v[38:41], v[66:69], v[112:115], v[38:41]
	global_load_lds_dwordx4 v[14:15], off
	v_lshl_add_u64 v[14:15], v[0:1], 0, s[50:51]
	s_mov_b32 m0, s48
	v_mfma_f32_16x16x32_bf16 v[50:53], v[66:69], v[88:91], v[50:53]
	global_load_lds_dwordx4 v[14:15], off
	s_mov_b64 s[46:47], 0x380
	v_mfma_f32_16x16x32_bf16 v[70:73], v[66:69], v[104:107], v[70:73]
	v_lshl_add_u64 v[14:15], v[2:3], 0, s[46:47]
	s_mov_b32 m0, s43
	v_readfirstlane_b32 s43, v6
	v_mfma_f32_16x16x32_bf16 v[10:13], v[66:69], v[108:111], v[10:13]
	ds_read_b128 v[66:69], v117 offset:0
	s_mov_b32 s50, 4
	v_mfma_f32_16x16x32_bf16 v[54:57], v[92:95], v[88:91], v[54:57]
	v_mfma_f32_16x16x32_bf16 v[62:65], v[96:99], v[88:91], v[62:65]
	v_mfma_f32_16x16x32_bf16 v[34:37], v[100:103], v[88:91], v[34:37]
	ds_read_b128 v[88:91], v117 offset:1024
	v_mfma_f32_16x16x32_bf16 v[42:45], v[92:95], v[112:115], v[42:45]
	v_mfma_f32_16x16x32_bf16 v[76:79], v[92:95], v[104:107], v[76:79]
	v_mfma_f32_16x16x32_bf16 v[18:21], v[92:95], v[108:111], v[18:21]
	ds_read_b128 v[92:95], v117 offset:2048
	v_mfma_f32_16x16x32_bf16 v[46:49], v[96:99], v[112:115], v[46:49]
	v_mfma_f32_16x16x32_bf16 v[80:83], v[96:99], v[104:107], v[80:83]
	v_mfma_f32_16x16x32_bf16 v[58:61], v[100:103], v[104:107], v[58:61]
	ds_read_b128 v[104:107], v117 offset:3072
	v_mfma_f32_16x16x32_bf16 v[30:33], v[100:103], v[112:115], v[30:33]
	ds_read_b128 v[112:115], v116 offset:0
	v_mfma_f32_16x16x32_bf16 v[22:25], v[96:99], v[108:111], v[22:25]
	ds_read_b128 v[96:99], v116 offset:1024
	s_nop 0
	s_waitcnt lgkmcnt(0)
	v_mfma_f32_16x16x32_bf16 v[26:29], v[100:103], v[108:111], v[26:29]
	v_mfma_f32_16x16x32_bf16 v[100:103], v[92:95], v[112:115], v[46:49]
	ds_read_b128 v[46:49], v116 offset:2048
	ds_read_b128 v[108:111], v116 offset:3072
	s_nop 0
	s_waitcnt lgkmcnt(0)
	s_waitcnt vmcnt(12)
	s_barrier
	global_load_lds_dwordx4 v[14:15], off
	v_lshl_add_u64 v[14:15], v[4:5], 0, s[46:47]
	s_mov_b32 m0, s44
	v_mfma_f32_16x16x32_bf16 v[38:41], v[66:69], v[112:115], v[38:41]
	global_load_lds_dwordx4 v[14:15], off
	v_lshl_add_u64 v[14:15], v[0:1], 0, s[46:47]
	s_mov_b32 m0, s45
	v_mfma_f32_16x16x32_bf16 v[42:45], v[88:91], v[112:115], v[42:45]
	global_load_lds_dwordx4 v[14:15], off
	ds_read_b128 v[116:119], v125 offset:0
	ds_read_b128 v[120:123], v125 offset:1024
	ds_read_b128 v[136:139], v125 offset:2048
	ds_read_b128 v[140:143], v125 offset:3072
	v_mfma_f32_16x16x32_bf16 v[30:33], v[104:107], v[112:115], v[30:33]
	s_mov_b64 s[44:45], 0x3c0
	v_lshl_add_u64 v[2:3], v[2:3], 0, s[44:45]
	s_mov_b32 m0, s43
	v_mfma_f32_16x16x32_bf16 v[112:115], v[66:69], v[108:111], v[10:13]
	ds_read_b128 v[10:13], v124 offset:0
	v_readfirstlane_b32 s43, v7
	v_lshl_add_u64 v[0:1], v[0:1], 0, s[44:45]
	v_mfma_f32_16x16x32_bf16 v[50:53], v[66:69], v[96:99], v[50:53]
	v_mfma_f32_16x16x32_bf16 v[70:73], v[66:69], v[46:49], v[70:73]
	ds_read_b128 v[66:69], v124 offset:1024
	s_nop 0
	s_waitcnt lgkmcnt(0)
	v_mfma_f32_16x16x32_bf16 v[54:57], v[88:91], v[96:99], v[54:57]
	v_mfma_f32_16x16x32_bf16 v[62:65], v[92:95], v[96:99], v[62:65]
	v_mfma_f32_16x16x32_bf16 v[96:99], v[104:107], v[96:99], v[34:37]
	v_mfma_f32_16x16x32_bf16 v[34:37], v[136:139], v[10:13], v[100:103]
	ds_read_b128 v[100:103], v124 offset:2048
	v_mfma_f32_16x16x32_bf16 v[76:79], v[88:91], v[46:49], v[76:79]
	v_mfma_f32_16x16x32_bf16 v[80:83], v[92:95], v[46:49], v[80:83]
	v_mfma_f32_16x16x32_bf16 v[58:61], v[104:107], v[46:49], v[58:61]
	v_mfma_f32_16x16x32_bf16 v[88:91], v[88:91], v[108:111], v[18:21]
	v_mfma_f32_16x16x32_bf16 v[92:95], v[92:95], v[108:111], v[22:25]
	v_mfma_f32_16x16x32_bf16 v[104:107], v[104:107], v[108:111], v[26:29]
	ds_read_b128 v[108:111], v124 offset:3072
	s_nop 0
	s_waitcnt lgkmcnt(0)
	s_waitcnt vmcnt(12)
	s_barrier
	global_load_lds_dwordx4 v[2:3], off
	v_lshl_add_u64 v[2:3], v[4:5], 0, s[44:45]
	s_mov_b32 m0, s43
	v_readfirstlane_b32 s43, v8
	global_load_lds_dwordx4 v[2:3], off
	s_mov_b32 m0, s43
	v_mfma_f32_16x16x32_bf16 v[46:49], v[116:119], v[10:13], v[38:41]
	global_load_lds_dwordx4 v[0:1], off
	ds_read_b128 v[0:3], v144 offset:0
	v_mfma_f32_16x16x32_bf16 v[38:41], v[136:139], v[66:69], v[62:65]
	ds_read_b128 v[4:7], v144 offset:1024
	v_mad_i64_i32 v[84:85], s[44:45], v75, s33, 0
	v_mfma_f32_16x16x32_bf16 v[62:65], v[136:139], v[100:103], v[80:83]
	s_mov_b32 s43, 10
	s_nop 1
	v_add_u32_e32 v82, 0x80, v75
	v_mfma_f32_16x16x32_bf16 v[42:45], v[120:123], v[10:13], v[42:45]
	v_mad_i64_i32 v[82:83], s[44:45], v82, s33, 0
	v_readlane_b32 s44, v252, 19
	v_mfma_f32_16x16x32_bf16 v[22:25], v[140:143], v[10:13], v[30:33]
	ds_read_b128 v[8:11], v144 offset:2048
	ds_read_b128 v[12:15], v144 offset:3072
	v_readlane_b32 s45, v252, 20
	v_mfma_f32_16x16x32_bf16 v[26:29], v[140:143], v[66:69], v[96:99]
	s_nop 2
	v_lshlrev_b32_e32 v96, 4, v74
	v_mfma_f32_16x16x32_bf16 v[18:21], v[120:123], v[66:69], v[54:57]
	ds_read_b128 v[54:57], v135 offset:0
	v_or_b32_e32 v84, v84, v96
	v_or_b32_e32 v82, v82, v96
	v_or_b32_e32 v86, v86, v96
	v_mfma_f32_16x16x32_bf16 v[30:33], v[116:119], v[66:69], v[50:53]
	ds_read_b128 v[50:53], v135 offset:1024
	s_nop 0
	s_waitcnt lgkmcnt(0)
	v_mfma_f32_16x16x32_bf16 v[70:73], v[116:119], v[100:103], v[70:73]
	v_mfma_f32_16x16x32_bf16 v[66:69], v[120:123], v[100:103], v[76:79]
	v_mfma_f32_16x16x32_bf16 v[58:61], v[140:143], v[100:103], v[58:61]
	v_mfma_f32_16x16x32_bf16 v[78:81], v[116:119], v[108:111], v[112:115]
	v_lshl_add_u64 v[116:117], s[40:41], 0, v[82:83]
	v_lshl_add_u64 v[118:119], s[44:45], 0, v[86:87]
	s_mov_b64 s[44:45], 0
	v_lshl_add_u64 v[114:115], s[40:41], 0, v[84:85]
	v_mfma_f32_16x16x32_bf16 v[74:77], v[120:123], v[108:111], v[88:91]
	v_mfma_f32_16x16x32_bf16 v[82:85], v[136:139], v[108:111], v[92:95]
	v_mfma_f32_16x16x32_bf16 v[86:89], v[140:143], v[108:111], v[104:107]
	s_branch .LBB0_969

.LBB0_1152:
	s_or_b64 exec, exec, s[40:41]
	s_waitcnt lgkmcnt(0)
	s_setprio 0
	s_barrier
	ds_read_b32 v0, v230
	s_waitcnt lgkmcnt(0)
	v_cmp_gt_i32_e32 vcc, 0, v0
	v_readfirstlane_b32 s40, v0
	s_cbranch_vccnz .LBB0_1174
	v_mov_b32_e32 v203, v195
	v_readfirstlane_b32 s43, v195
	s_cmpk_lt_u32 s43, 0x100
	s_cbranch_scc1 .Lprio_m1
	s_setprio 1
.Lprio_m1:
	s_lshl_b32 s34, s40, 2
	s_lshl_b32 s40, s40, 8
	s_and_b32 s43, s40, 0x3f00
	v_lshrrev_b32_e32 v1, 1, v203
	s_movk_i32 s40, 0x78
	v_and_b32_e32 v1, 6, v1
	v_bfe_u32 v201, v203, 4, 2
	v_lshrrev_b32_e64 v1, v1, s40
	v_bitop3_b32 v1, v1, v201, 3 bitop3:0x6c
	v_lshlrev_b32_e32 v0, 1, v201
	v_lshlrev_b32_e32 v20, 4, v1
	v_ashrrev_i32_e32 v1, 1, v203
	v_ashrrev_i32_e32 v10, 6, v203
	v_lshrrev_b32_e64 v18, v0, s40
	v_and_b32_e32 v238, 15, v203
	v_and_b32_e32 v239, 0xffffff80, v1
	s_and_b32 s34, s34, 0x7fffff00
	v_xor_b32_e32 v0, v18, v203
	v_bfe_u32 v19, v203, 2, 4
	v_or_b32_e32 v1, v239, v238
	v_lshlrev_b32_e32 v4, 4, v10
	v_lshl_or_b32 v240, v1, 6, v20
	v_lshlrev_b32_e32 v1, 6, v203
	v_lshlrev_b32_e32 v0, 4, v0
	v_ashrrev_i32_e32 v5, 31, v4
	v_or_b32_e32 v6, s34, v19
	v_mov_b32_e32 v7, v17
	v_and_b32_e32 v21, 0x33c0, v1
	v_and_b32_e32 v0, 48, v0
	v_mov_b32_e32 v1, v17
	v_lshl_add_u64 v[8:9], v[6:7], 0, v[4:5]
	v_lshlrev_b32_e32 v241, 10, v10
	v_lshl_add_u64 v[2:3], s[4:5], 0, v[0:1]
	v_lshlrev_b64 v[8:9], 6, v[8:9]
	v_readfirstlane_b32 s40, v241
	v_lshl_add_u64 v[8:9], v[2:3], 0, v[8:9]
	s_mov_b32 m0, s40
	v_add_u32_e32 v12, 8, v10
	global_load_lds_dwordx4 v[8:9], off
	v_lshlrev_b32_e32 v8, 4, v12
	v_ashrrev_i32_e32 v9, 31, v8
	v_lshl_add_u64 v[10:11], v[6:7], 0, v[8:9]
	v_lshlrev_b32_e32 v242, 10, v12
	v_lshlrev_b64 v[10:11], 6, v[10:11]
	v_readfirstlane_b32 s40, v242
	v_lshl_add_u64 v[10:11], v[2:3], 0, v[10:11]
	s_mov_b32 m0, s40
	v_add_u32_e32 v7, 0x4000, v241
	global_load_lds_dwordx4 v[10:11], off
	v_or_b32_e32 v10, s43, v19
	v_mov_b32_e32 v11, v17
	v_lshl_add_u64 v[12:13], v[10:11], 0, v[4:5]
	v_lshl_add_u64 v[0:1], s[58:59], 0, v[0:1]
	v_lshlrev_b64 v[12:13], 6, v[12:13]
	v_readfirstlane_b32 s40, v7
	v_lshl_add_u64 v[12:13], v[0:1], 0, v[12:13]
	s_mov_b32 m0, s40
	v_add_u32_e32 v7, 0x4000, v242
	global_load_lds_dwordx4 v[12:13], off
	v_lshl_add_u64 v[12:13], v[10:11], 0, v[8:9]
	v_lshlrev_b64 v[12:13], 6, v[12:13]
	v_readfirstlane_b32 s40, v7
	v_lshl_add_u64 v[12:13], v[0:1], 0, v[12:13]
	s_mov_b32 m0, s40
	s_add_i32 s40, s34, 0x9000
	global_load_lds_dwordx4 v[12:13], off
	v_or_b32_e32 v12, s40, v19
	v_mov_b32_e32 v13, v17
	v_lshl_add_u64 v[14:15], v[12:13], 0, v[4:5]
	v_add_u32_e32 v7, 0x8000, v241
	v_lshlrev_b64 v[14:15], 6, v[14:15]
	v_readfirstlane_b32 s40, v7
	v_lshl_add_u64 v[12:13], v[12:13], 0, v[8:9]
	v_add_u32_e32 v7, 0x8000, v242
	v_lshl_add_u64 v[14:15], v[2:3], 0, v[14:15]
	s_mov_b32 m0, s40
	v_lshlrev_b64 v[12:13], 6, v[12:13]
	v_readfirstlane_b32 s40, v7
	global_load_lds_dwordx4 v[14:15], off
	v_lshl_add_u64 v[12:13], v[2:3], 0, v[12:13]
	s_mov_b32 m0, s40
	s_add_i32 s40, s43, 0x1000
	global_load_lds_dwordx4 v[12:13], off
	v_or_b32_e32 v12, s40, v19
	v_mov_b32_e32 v13, v17
	v_lshl_add_u64 v[14:15], v[12:13], 0, v[4:5]
	v_add_u32_e32 v7, 0xc000, v241
	v_lshlrev_b64 v[14:15], 6, v[14:15]
	v_readfirstlane_b32 s40, v7
	v_lshl_add_u64 v[12:13], v[12:13], 0, v[8:9]
	v_add_u32_e32 v7, 0xc000, v242
	v_lshl_add_u64 v[14:15], v[0:1], 0, v[14:15]
	s_mov_b32 m0, s40
	v_lshlrev_b64 v[12:13], 6, v[12:13]
	v_readfirstlane_b32 s40, v7
	global_load_lds_dwordx4 v[14:15], off
	v_lshl_add_u64 v[12:13], v[0:1], 0, v[12:13]
	s_mov_b32 m0, s40
	s_add_i32 s40, s34, 0x12000
	global_load_lds_dwordx4 v[12:13], off
	v_or_b32_e32 v12, s40, v19
	v_mov_b32_e32 v13, v17
	v_lshl_add_u64 v[14:15], v[12:13], 0, v[4:5]
	v_add_u32_e32 v7, 0x10000, v241
	v_lshlrev_b64 v[14:15], 6, v[14:15]
	v_readfirstlane_b32 s40, v7
	v_lshl_add_u64 v[12:13], v[12:13], 0, v[8:9]
	v_add_u32_e32 v7, 0x10000, v242
	v_lshl_add_u64 v[14:15], v[2:3], 0, v[14:15]
	s_mov_b32 m0, s40
	v_lshlrev_b64 v[12:13], 6, v[12:13]
	v_readfirstlane_b32 s40, v7
	global_load_lds_dwordx4 v[14:15], off
	v_lshl_add_u64 v[12:13], v[2:3], 0, v[12:13]
	s_mov_b32 m0, s40
	s_add_i32 s40, s43, 0x2000
	global_load_lds_dwordx4 v[12:13], off
	v_or_b32_e32 v12, s40, v19
	v_mov_b32_e32 v13, v17
	v_lshl_add_u64 v[14:15], v[12:13], 0, v[4:5]
	v_add_u32_e32 v7, 0x14000, v241
	v_lshlrev_b64 v[14:15], 6, v[14:15]
	v_readfirstlane_b32 s40, v7
	v_lshl_add_u64 v[12:13], v[12:13], 0, v[8:9]
	v_add_u32_e32 v7, 0x14000, v242
	v_lshl_add_u64 v[14:15], v[0:1], 0, v[14:15]
	s_mov_b32 m0, s40
	v_lshlrev_b64 v[12:13], 6, v[12:13]
	v_readfirstlane_b32 s40, v7
	global_load_lds_dwordx4 v[14:15], off
	v_lshl_add_u64 v[12:13], v[0:1], 0, v[12:13]
	s_mov_b32 m0, s40
	s_add_i32 s40, s34, 0x1b000
	global_load_lds_dwordx4 v[12:13], off
	v_or_b32_e32 v12, s40, v19
	v_mov_b32_e32 v13, v17
	v_lshl_add_u64 v[14:15], v[12:13], 0, v[4:5]
	v_add_u32_e32 v7, 0x18000, v241
	v_lshlrev_b64 v[14:15], 6, v[14:15]
	v_readfirstlane_b32 s40, v7
	v_lshl_add_u64 v[12:13], v[12:13], 0, v[8:9]
	v_add_u32_e32 v7, 0x18000, v242
	v_lshl_add_u64 v[14:15], v[2:3], 0, v[14:15]
	s_mov_b32 m0, s40
	v_lshlrev_b64 v[12:13], 6, v[12:13]
	v_readfirstlane_b32 s40, v7
	global_load_lds_dwordx4 v[14:15], off
	v_lshl_add_u64 v[2:3], v[2:3], 0, v[12:13]
	s_mov_b32 m0, s40
	s_add_i32 s40, s43, 0x3000
	global_load_lds_dwordx4 v[2:3], off
	v_or_b32_e32 v2, s40, v19
	v_mov_b32_e32 v3, v17
	v_lshl_add_u64 v[12:13], v[2:3], 0, v[4:5]
	v_lshl_add_u64 v[2:3], v[2:3], 0, v[8:9]
	v_lshlrev_b64 v[12:13], 6, v[12:13]
	v_add_u32_e32 v7, 0x1c000, v241
	v_lshlrev_b64 v[2:3], 6, v[2:3]
	v_lshl_add_u64 v[12:13], v[0:1], 0, v[12:13]
	v_readfirstlane_b32 s40, v7
	v_lshl_add_u64 v[0:1], v[0:1], 0, v[2:3]
	v_add_u32_e32 v2, 0x1c000, v242
	s_mov_b32 m0, s40
	v_readfirstlane_b32 s40, v2
	global_load_lds_dwordx4 v[12:13], off
	s_mov_b32 m0, s40
	s_movk_i32 s40, 0x4000
	global_load_lds_dwordx4 v[0:1], off
	v_bitop3_b32 v0, v18, 3, v203 bitop3:0x48
	v_lshlrev_b32_e32 v206, 4, v0
	v_add_u32_e32 v0, 0x5000, v10
	v_mov_b32_e32 v1, v17
	v_or3_b32 v243, v21, v20, s40
	v_lshl_add_u64 v[0:1], v[4:5], 0, v[0:1]
	v_readlane_b32 s40, v252, 19
	s_waitcnt vmcnt(12)
	s_barrier
	ds_read_b128 v[70:73], v243 offset:0
	v_lshlrev_b64 v[0:1], 6, v[0:1]
	v_readlane_b32 s41, v252, 20
	ds_read_b128 v[78:81], v243 offset:1024
	ds_read_b128 v[82:85], v243 offset:2048
	ds_read_b128 v[86:89], v243 offset:3072
	ds_read_b128 v[130:133], v240 offset:0
	ds_read_b128 v[126:129], v240 offset:1024
	s_nop 1
	v_lshl_add_u64 v[208:209], s[40:41], 0, v[0:1]
	v_add_u32_e32 v0, 0x2d000, v6
	v_mov_b32_e32 v1, v17
	v_lshl_add_u64 v[0:1], v[4:5], 0, v[0:1]
	v_lshlrev_b64 v[0:1], 6, v[0:1]
	v_lshl_add_u64 v[210:211], s[40:41], 0, v[0:1]
	v_or_b32_e32 v0, 0x4000, v10
	v_mov_b32_e32 v1, v17
	v_lshl_add_u64 v[0:1], v[4:5], 0, v[0:1]
	ds_read_b128 v[122:125], v240 offset:2048
	v_lshlrev_b64 v[0:1], 6, v[0:1]
	ds_read_b128 v[118:121], v240 offset:3072
	v_lshl_add_u64 v[212:213], s[40:41], 0, v[0:1]
	v_add_u32_e32 v0, 0x24000, v6
	v_mov_b32_e32 v1, v17
	s_waitcnt lgkmcnt(0)
	v_lshl_add_u64 v[0:1], v[4:5], 0, v[0:1]
	v_lshlrev_b64 v[0:1], 6, v[0:1]
	v_mov_b32_e32 v8, 0
	v_mov_b32_e32 v207, v17
	v_lshl_add_u64 v[214:215], s[40:41], 0, v[0:1]
	s_mov_b32 s46, 0
	s_mov_b32 s48, 29
	s_mov_b32 s49, 0
	v_mov_b32_e32 v9, v8
	v_mov_b32_e32 v10, v8
	v_mov_b32_e32 v11, v8
	v_mov_b32_e32 v22, v8
	v_mov_b32_e32 v23, v8
	v_mov_b32_e32 v24, v8
	v_mov_b32_e32 v25, v8
	v_mov_b32_e32 v26, v8
	v_mov_b32_e32 v27, v8
	v_mov_b32_e32 v28, v8
	v_mov_b32_e32 v29, v8
	v_mov_b32_e32 v0, v8
	v_mov_b32_e32 v1, v8
	v_mov_b32_e32 v2, v8
	v_mov_b32_e32 v3, v8
	v_mov_b32_e32 v4, v8
	v_mov_b32_e32 v5, v8
	v_mov_b32_e32 v6, v8
	v_mov_b32_e32 v7, v8
	v_mov_b32_e32 v12, v8
	v_mov_b32_e32 v13, v8
	v_mov_b32_e32 v14, v8
	v_mov_b32_e32 v15, v8
	v_mov_b32_e32 v18, v8
	v_mov_b32_e32 v19, v8
	v_mov_b32_e32 v20, v8
	v_mov_b32_e32 v21, v8
	v_mov_b32_e32 v30, v8
	v_mov_b32_e32 v31, v8
	v_mov_b32_e32 v32, v8
	v_mov_b32_e32 v33, v8
	v_mov_b32_e32 v34, v8
	v_mov_b32_e32 v35, v8
	v_mov_b32_e32 v36, v8
	v_mov_b32_e32 v37, v8
	v_mov_b32_e32 v38, v8
	v_mov_b32_e32 v39, v8
	v_mov_b32_e32 v40, v8
	v_mov_b32_e32 v41, v8
	v_mov_b32_e32 v42, v8
	v_mov_b32_e32 v43, v8
	v_mov_b32_e32 v44, v8
	v_mov_b32_e32 v45, v8
	v_mov_b32_e32 v46, v8
	v_mov_b32_e32 v47, v8
	v_mov_b32_e32 v48, v8
	v_mov_b32_e32 v49, v8
	v_mov_b32_e32 v50, v8
	v_mov_b32_e32 v51, v8
	v_mov_b32_e32 v52, v8
	v_mov_b32_e32 v53, v8
	v_mov_b32_e32 v54, v8
	v_mov_b32_e32 v55, v8
	v_mov_b32_e32 v56, v8
	v_mov_b32_e32 v57, v8
	v_mov_b32_e32 v58, v8
	v_mov_b32_e32 v59, v8
	v_mov_b32_e32 v60, v8
	v_mov_b32_e32 v61, v8
	v_mov_b32_e32 v62, v8
	v_mov_b32_e32 v63, v8
	v_mov_b32_e32 v64, v8
	v_mov_b32_e32 v65, v8
	v_mov_b32_e32 v66, v8
	v_mov_b32_e32 v67, v8
	v_mov_b32_e32 v68, v8
	v_mov_b32_e32 v69, v8
	v_mov_b32_e32 v74, v8
	v_mov_b32_e32 v75, v8
	v_mov_b32_e32 v76, v8
	v_mov_b32_e32 v77, v8
	v_mov_b32_e32 v90, v8
	v_mov_b32_e32 v91, v8
	v_mov_b32_e32 v92, v8
	v_mov_b32_e32 v93, v8
	v_mov_b32_e32 v94, v8
	v_mov_b32_e32 v95, v8
	v_mov_b32_e32 v96, v8
	v_mov_b32_e32 v97, v8
	v_mov_b32_e32 v98, v8
	v_mov_b32_e32 v99, v8
	v_mov_b32_e32 v100, v8
	v_mov_b32_e32 v101, v8
	v_mov_b32_e32 v102, v8
	v_mov_b32_e32 v103, v8
	v_mov_b32_e32 v104, v8
	v_mov_b32_e32 v105, v8
	v_mov_b32_e32 v106, v8
	v_mov_b32_e32 v107, v8
	v_mov_b32_e32 v108, v8
	v_mov_b32_e32 v109, v8
	v_mov_b32_e32 v110, v8
	v_mov_b32_e32 v111, v8
	v_mov_b32_e32 v112, v8
	v_mov_b32_e32 v113, v8
	v_mov_b32_e32 v114, v8
	v_mov_b32_e32 v115, v8
	v_mov_b32_e32 v116, v8
	v_mov_b32_e32 v117, v8
	v_mov_b32_e32 v134, v8
	v_mov_b32_e32 v135, v8
	v_mov_b32_e32 v136, v8
	v_mov_b32_e32 v137, v8
	v_mov_b32_e32 v138, v8
	v_mov_b32_e32 v139, v8
	v_mov_b32_e32 v140, v8
	v_mov_b32_e32 v141, v8
	v_mov_b32_e32 v142, v8
	v_mov_b32_e32 v143, v8
	v_mov_b32_e32 v144, v8
	v_mov_b32_e32 v145, v8
	v_mov_b32_e32 v146, v8
	v_mov_b32_e32 v147, v8
	v_mov_b32_e32 v148, v8
	v_mov_b32_e32 v149, v8
	v_mov_b32_e32 v150, v8
	v_mov_b32_e32 v151, v8
	v_mov_b32_e32 v152, v8
	v_mov_b32_e32 v153, v8
	v_mov_b32_e32 v154, v8
	v_mov_b32_e32 v155, v8
	v_mov_b32_e32 v156, v8
	v_mov_b32_e32 v157, v8
	v_mov_b32_e32 v158, v8
	v_mov_b32_e32 v159, v8
	v_mov_b32_e32 v160, v8
	v_mov_b32_e32 v161, v8
	v_readfirstlane_b32 s100, v241
	v_readfirstlane_b32 s101, v242
	s_branch .LBB0_1155

.LBB0_1253:
	s_or_b64 exec, exec, s[40:41]
	s_waitcnt lgkmcnt(0)
	s_setprio 0
	s_barrier
	ds_read_b32 v0, v230
	s_waitcnt lgkmcnt(0)
	v_cmp_gt_i32_e32 vcc, 0, v0
	v_readfirstlane_b32 s40, v0
	s_cbranch_vccnz .LBB0_1285
	v_mov_b32_e32 v126, v195
	v_readfirstlane_b32 s41, v195
	s_cmpk_lt_u32 s41, 0x100
	s_cbranch_scc1 .Lprio_m2
	s_setprio 1
.Lprio_m2:
	s_movk_i32 s41, 0x78
	v_lshrrev_b32_e32 v1, 1, v126
	v_and_b32_e32 v1, 6, v1
	v_bfe_u32 v125, v126, 4, 2
	v_lshrrev_b32_e64 v1, v1, s41
	v_bitop3_b32 v1, v1, v125, 3 bitop3:0x6c
	v_lshlrev_b32_e32 v0, 1, v125
	v_lshlrev_b32_e32 v11, 4, v1
	v_ashrrev_i32_e32 v1, 1, v126
	s_lshl_b32 s34, s40, 2
	v_ashrrev_i32_e32 v6, 6, v126
	v_lshrrev_b32_e64 v32, v0, s41
	v_and_b32_e32 v127, 15, v126
	v_and_b32_e32 v128, 0xffffffc0, v1
	s_and_b32 s43, s34, 0x7fffff00
	v_xor_b32_e32 v0, v32, v126
	v_bfe_u32 v10, v126, 2, 4
	v_or_b32_e32 v1, v128, v127
	v_lshlrev_b32_e32 v26, 4, v6
	v_lshl_or_b32 v129, v1, 6, v11
	v_lshlrev_b32_e32 v1, 6, v126
	v_lshlrev_b32_e32 v0, 4, v0
	v_ashrrev_i32_e32 v27, 31, v26
	v_or_b32_e32 v30, s43, v10
	v_mov_b32_e32 v31, v17
	v_and_b32_e32 v12, 0x13c0, v1
	v_and_b32_e32 v0, 48, v0
	v_mov_b32_e32 v1, v17
	v_lshlrev_b32_e32 v130, 10, v6
	v_lshl_add_u64 v[4:5], v[30:31], 0, v[26:27]
	v_lshl_add_u64 v[2:3], s[30:31], 0, v[0:1]
	v_lshlrev_b64 v[4:5], 6, v[4:5]
	v_readfirstlane_b32 s41, v130
	v_lshl_add_u64 v[4:5], v[2:3], 0, v[4:5]
	s_mov_b32 m0, s41
	v_add_u32_e32 v8, 8, v6
	global_load_lds_dwordx4 v[4:5], off
	v_lshlrev_b32_e32 v4, 4, v8
	v_ashrrev_i32_e32 v5, 31, v4
	v_lshl_add_u64 v[6:7], v[30:31], 0, v[4:5]
	v_lshlrev_b32_e32 v131, 10, v8
	s_lshl_b32 s34, s40, 7
	v_lshlrev_b64 v[6:7], 6, v[6:7]
	v_readfirstlane_b32 s41, v131
	s_and_b32 s34, s34, 0x1f80
	v_or_b32_e32 v28, v26, v10
	v_mov_b32_e32 v29, v27
	v_lshl_add_u64 v[6:7], v[2:3], 0, v[6:7]
	s_mov_b32 m0, s41
	v_add_u32_e32 v8, 0x4000, v130
	global_load_lds_dwordx4 v[6:7], off
	v_lshl_add_u64 v[6:7], v[28:29], 0, s[34:35]
	v_lshl_add_u64 v[0:1], s[56:57], 0, v[0:1]
	v_lshlrev_b64 v[6:7], 6, v[6:7]
	v_readfirstlane_b32 s41, v8
	v_lshl_add_u64 v[6:7], v[0:1], 0, v[6:7]
	s_mov_b32 m0, s41
	s_add_i32 s41, s43, 0x9000
	global_load_lds_dwordx4 v[6:7], off
	v_or_b32_e32 v6, s41, v10
	v_mov_b32_e32 v7, v17
	v_lshl_add_u64 v[8:9], v[6:7], 0, v[26:27]
	v_add_u32_e32 v13, 0x6000, v130
	v_lshlrev_b64 v[8:9], 6, v[8:9]
	v_readfirstlane_b32 s41, v13
	v_lshl_add_u64 v[8:9], v[2:3], 0, v[8:9]
	s_mov_b32 m0, s41
	v_lshl_add_u64 v[6:7], v[6:7], 0, v[4:5]
	global_load_lds_dwordx4 v[8:9], off
	v_add_u32_e32 v8, 0x6000, v131
	v_lshlrev_b64 v[6:7], 6, v[6:7]
	v_readfirstlane_b32 s41, v8
	v_lshl_add_u64 v[6:7], v[2:3], 0, v[6:7]
	s_mov_b32 m0, s41
	s_add_i32 s44, s34, 0x400
	s_mov_b32 s45, s35
	global_load_lds_dwordx4 v[6:7], off
	v_lshl_add_u64 v[6:7], v[28:29], 0, s[44:45]
	v_add_u32_e32 v8, 0xa000, v130
	v_lshlrev_b64 v[6:7], 6, v[6:7]
	v_readfirstlane_b32 s41, v8
	v_lshl_add_u64 v[6:7], v[0:1], 0, v[6:7]
	s_mov_b32 m0, s41
	s_add_i32 s41, s43, 0x12000
	global_load_lds_dwordx4 v[6:7], off
	v_or_b32_e32 v6, s41, v10
	v_mov_b32_e32 v7, v17
	v_lshl_add_u64 v[8:9], v[6:7], 0, v[26:27]
	v_add_u32_e32 v13, 0xc000, v130
	v_lshlrev_b64 v[8:9], 6, v[8:9]
	v_readfirstlane_b32 s41, v13
	v_lshl_add_u64 v[8:9], v[2:3], 0, v[8:9]
	s_mov_b32 m0, s41
	v_lshl_add_u64 v[6:7], v[6:7], 0, v[4:5]
	global_load_lds_dwordx4 v[8:9], off
	v_add_u32_e32 v8, 0xc000, v131
	v_lshlrev_b64 v[6:7], 6, v[6:7]
	v_readfirstlane_b32 s41, v8
	v_lshl_add_u64 v[6:7], v[2:3], 0, v[6:7]
	s_mov_b32 m0, s41
	s_add_i32 s44, s34, 0x800
	global_load_lds_dwordx4 v[6:7], off
	v_lshl_add_u64 v[6:7], v[28:29], 0, s[44:45]
	v_add_u32_e32 v8, 0x10000, v130
	v_lshlrev_b64 v[6:7], 6, v[6:7]
	v_readfirstlane_b32 s41, v8
	v_lshl_add_u64 v[6:7], v[0:1], 0, v[6:7]
	s_mov_b32 m0, s41
	s_add_i32 s41, s43, 0x1b000
	global_load_lds_dwordx4 v[6:7], off
	v_or_b32_e32 v6, s41, v10
	v_mov_b32_e32 v7, v17
	v_lshl_add_u64 v[8:9], v[6:7], 0, v[26:27]
	v_add_u32_e32 v13, 0x12000, v130
	v_lshlrev_b64 v[8:9], 6, v[8:9]
	v_readfirstlane_b32 s41, v13
	v_lshl_add_u64 v[8:9], v[2:3], 0, v[8:9]
	s_mov_b32 m0, s41
	v_lshl_add_u64 v[6:7], v[6:7], 0, v[4:5]
	global_load_lds_dwordx4 v[8:9], off
	v_add_u32_e32 v8, 0x12000, v131
	v_lshlrev_b64 v[6:7], 6, v[6:7]
	v_readfirstlane_b32 s41, v8
	v_lshl_add_u64 v[6:7], v[2:3], 0, v[6:7]
	s_mov_b32 m0, s41
	s_add_i32 s44, s34, 0xc00
	global_load_lds_dwordx4 v[6:7], off
	v_lshl_add_u64 v[6:7], v[28:29], 0, s[44:45]
	v_add_u32_e32 v8, 0x16000, v130
	v_lshlrev_b64 v[6:7], 6, v[6:7]
	v_readfirstlane_b32 s41, v8
	v_lshl_add_u64 v[6:7], v[0:1], 0, v[6:7]
	s_mov_b32 m0, s41
	s_add_i32 s41, s43, 0x24000
	global_load_lds_dwordx4 v[6:7], off
	v_or_b32_e32 v6, s41, v10
	v_mov_b32_e32 v7, v17
	v_lshl_add_u64 v[8:9], v[6:7], 0, v[26:27]
	v_add_u32_e32 v13, 0x18000, v130
	v_lshlrev_b64 v[8:9], 6, v[8:9]
	v_readfirstlane_b32 s41, v13
	v_lshl_add_u64 v[8:9], v[2:3], 0, v[8:9]
	s_mov_b32 m0, s41
	v_lshl_add_u64 v[6:7], v[6:7], 0, v[4:5]
	global_load_lds_dwordx4 v[8:9], off
	v_add_u32_e32 v8, 0x18000, v131
	v_lshlrev_b64 v[6:7], 6, v[6:7]
	v_readfirstlane_b32 s41, v8
	v_lshl_add_u64 v[6:7], v[2:3], 0, v[6:7]
	s_mov_b32 m0, s41
	s_add_i32 s44, s34, 0x1000
	global_load_lds_dwordx4 v[6:7], off
	v_lshl_add_u64 v[6:7], v[28:29], 0, s[44:45]
	v_add_u32_e32 v8, 0x1c000, v130
	v_lshlrev_b64 v[6:7], 6, v[6:7]
	v_readfirstlane_b32 s41, v8
	v_lshl_add_u64 v[6:7], v[0:1], 0, v[6:7]
	s_mov_b32 m0, s41
	s_add_i32 s41, s43, 0x2d000
	global_load_lds_dwordx4 v[6:7], off
	v_or_b32_e32 v6, s41, v10
	v_mov_b32_e32 v7, v17
	v_lshl_add_u64 v[8:9], v[6:7], 0, v[26:27]
	v_lshl_add_u64 v[4:5], v[6:7], 0, v[4:5]
	v_lshlrev_b64 v[8:9], 6, v[8:9]
	v_add_u32_e32 v10, 0x1e000, v130
	v_lshlrev_b64 v[4:5], 6, v[4:5]
	v_lshl_add_u64 v[8:9], v[2:3], 0, v[8:9]
	v_readfirstlane_b32 s41, v10
	v_lshl_add_u64 v[2:3], v[2:3], 0, v[4:5]
	v_add_u32_e32 v4, 0x1e000, v131
	s_mov_b32 m0, s41
	v_readfirstlane_b32 s41, v4
	global_load_lds_dwordx4 v[8:9], off
	s_mov_b32 m0, s41
	s_add_i32 s44, s34, 0x1400
	global_load_lds_dwordx4 v[2:3], off
	v_lshl_add_u64 v[2:3], v[28:29], 0, s[44:45]
	v_lshlrev_b64 v[2:3], 6, v[2:3]
	v_lshl_add_u64 v[0:1], v[0:1], 0, v[2:3]
	v_add_u32_e32 v2, 0x22000, v130
	s_and_b32 s40, s40, 63
	v_readfirstlane_b32 s41, v2
	s_mov_b32 m0, s41
	s_movk_i32 s41, 0x4000
	global_load_lds_dwordx4 v[0:1], off
	s_lshl_b32 s40, s40, 13
	v_readlane_b32 s44, v252, 19
	v_or3_b32 v132, v12, v11, s41
	s_waitcnt vmcnt(15)
	s_barrier
	ds_read_b128 v[0:3], v132 offset:0
	v_readlane_b32 s45, v252, 20
	s_add_u32 s40, s44, s40
	ds_read_b128 v[4:7], v132 offset:1024
	v_lshlrev_b64 v[28:29], 6, v[28:29]
	s_addc_u32 s41, s45, 0
	ds_read_b128 v[8:11], v132 offset:2048
	v_lshl_add_u64 v[116:117], s[40:41], 0, v[28:29]
	v_add_u32_e32 v28, 0x3f000, v30
	v_mov_b32_e32 v29, v17
	ds_read_b128 v[12:15], v132 offset:3072
	v_lshl_add_u64 v[28:29], v[26:27], 0, v[28:29]
	ds_read_b128 v[22:25], v129 offset:0
	v_lshlrev_b64 v[28:29], 6, v[28:29]
	ds_read_b128 v[18:21], v129 offset:1024
	v_lshl_add_u64 v[118:119], s[44:45], 0, v[28:29]
	v_add_u32_e32 v28, 0x36000, v30
	v_mov_b32_e32 v29, v17
	s_waitcnt lgkmcnt(0)
	v_lshl_add_u64 v[26:27], v[26:27], 0, v[28:29]
	v_bitop3_b32 v31, v32, 3, v126 bitop3:0x48
	v_lshlrev_b64 v[26:27], 6, v[26:27]
	v_mov_b32_e32 v58, 0
	v_lshlrev_b32_e32 v114, 4, v31
	v_mov_b32_e32 v115, v17
	v_lshl_add_u64 v[120:121], s[44:45], 0, v[26:27]
	s_mov_b32 s46, 0
	s_movk_i32 s52, 0x7d
	s_mov_b32 s53, 0
	v_mov_b32_e32 v59, v58
	v_mov_b32_e32 v60, v58
	v_mov_b32_e32 v61, v58
	v_mov_b32_e32 v78, v58
	v_mov_b32_e32 v79, v58
	v_mov_b32_e32 v80, v58
	v_mov_b32_e32 v81, v58
	v_mov_b32_e32 v30, v58
	v_mov_b32_e32 v31, v58
	v_mov_b32_e32 v32, v58
	v_mov_b32_e32 v33, v58
	v_mov_b32_e32 v26, v58
	v_mov_b32_e32 v27, v58
	v_mov_b32_e32 v28, v58
	v_mov_b32_e32 v29, v58
	v_mov_b32_e32 v42, v58
	v_mov_b32_e32 v43, v58
	v_mov_b32_e32 v44, v58
	v_mov_b32_e32 v45, v58
	v_mov_b32_e32 v50, v58
	v_mov_b32_e32 v51, v58
	v_mov_b32_e32 v52, v58
	v_mov_b32_e32 v53, v58
	v_mov_b32_e32 v62, v58
	v_mov_b32_e32 v63, v58
	v_mov_b32_e32 v64, v58
	v_mov_b32_e32 v65, v58
	v_mov_b32_e32 v70, v58
	v_mov_b32_e32 v71, v58
	v_mov_b32_e32 v72, v58
	v_mov_b32_e32 v73, v58
	v_mov_b32_e32 v34, v58
	v_mov_b32_e32 v35, v58
	v_mov_b32_e32 v36, v58
	v_mov_b32_e32 v37, v58
	v_mov_b32_e32 v38, v58
	v_mov_b32_e32 v39, v58
	v_mov_b32_e32 v40, v58
	v_mov_b32_e32 v41, v58
	v_mov_b32_e32 v46, v58
	v_mov_b32_e32 v47, v58
	v_mov_b32_e32 v48, v58
	v_mov_b32_e32 v49, v58
	v_mov_b32_e32 v54, v58
	v_mov_b32_e32 v55, v58
	v_mov_b32_e32 v56, v58
	v_mov_b32_e32 v57, v58
	v_mov_b32_e32 v66, v58
	v_mov_b32_e32 v67, v58
	v_mov_b32_e32 v68, v58
	v_mov_b32_e32 v69, v58
	v_mov_b32_e32 v74, v58
	v_mov_b32_e32 v75, v58
	v_mov_b32_e32 v76, v58
	v_mov_b32_e32 v77, v58
	v_mov_b32_e32 v82, v58
	v_mov_b32_e32 v83, v58
	v_mov_b32_e32 v84, v58
	v_mov_b32_e32 v85, v58
	v_mov_b32_e32 v86, v58
	v_mov_b32_e32 v87, v58
	v_mov_b32_e32 v88, v58
	v_mov_b32_e32 v89, v58
	v_readfirstlane_b32 s100, v130
	v_readfirstlane_b32 s101, v131
	s_branch .LBB0_1256
